# plus: sgu item group loop and sample-attention QK^T read their LDS fragments ahead of the MFMAs (batched / software-pipelined ds_reads)
# speedup vs baseline: 1.2083x; 1.0021x over previous
.LBB0_1163:
	v_lshl_add_u64 v[68:69], s[94:95], 0, v[44:45]
	v_add_co_u32_e32 v6, vcc, 0x2e80000, v68
	v_add_u32_e32 v10, s12, v98
	s_nop 0
	v_addc_co_u32_e32 v7, vcc, 0, v69, vcc
	global_load_dwordx4 v[2:5], v[6:7], off
	global_load_dwordx4 v[234:237], v[6:7], off offset:64
	global_load_dword v50, v[42:43], off
	global_load_dwordx2 v[66:67], v[46:47], off offset:-128
	global_load_dwordx2 v[64:65], v[46:47], off offset:-96
	global_load_dwordx2 v[62:63], v[46:47], off offset:-64
	global_load_dwordx2 v[60:61], v[46:47], off offset:-32
	global_load_dwordx2 v[58:59], v[46:47], off
	global_load_dwordx2 v[56:57], v[46:47], off offset:32
	global_load_dwordx2 v[54:55], v[46:47], off offset:64
	global_load_dwordx2 v[52:53], v[46:47], off offset:96
	global_load_dwordx4 v[38:41], v[6:7], off offset:128
	global_load_dwordx4 v[34:37], v[6:7], off offset:192
	v_add_u32_e32 v6, s12, v104
	ds_read_b128 v[6:9], v6
	ds_read_b128 v[10:13], v10
	v_add_u32_e32 v14, s12, v95
	v_add_u32_e32 v96, s12, v91
	s_andn2_b64 vcc, exec, s[4:5]
	s_waitcnt vmcnt(12) lgkmcnt(1)
	v_mfma_f32_16x16x32_bf16 v[30:33], v[6:9], v[2:5], 0
	ds_read_b128 v[6:9], v14
	v_add_u32_e32 v14, s12, v94
	s_waitcnt lgkmcnt(1)
	v_mfma_f32_16x16x32_bf16 v[26:29], v[10:13], v[2:5], 0
	ds_read_b128 v[10:13], v14
	v_add_u32_e32 v14, s12, v93
	s_waitcnt lgkmcnt(1)
	v_mfma_f32_16x16x32_bf16 v[22:25], v[6:9], v[2:5], 0
	ds_read_b128 v[6:9], v14
	v_add_u32_e32 v14, s12, v92
	s_waitcnt lgkmcnt(1)
	v_mfma_f32_16x16x32_bf16 v[18:21], v[10:13], v[2:5], 0
	ds_read_b128 v[10:13], v14
	s_waitcnt lgkmcnt(1)
	v_mfma_f32_16x16x32_bf16 v[14:17], v[6:9], v[2:5], 0
	ds_read_b128 v[6:9], v96
	v_add_u32_e32 v96, s12, v90
	ds_read_b128 v[108:111], v96
	s_waitcnt lgkmcnt(2)
	v_mfma_f32_16x16x32_bf16 v[10:13], v[10:13], v[2:5], 0
	s_waitcnt lgkmcnt(1)
	v_mfma_f32_16x16x32_bf16 v[6:9], v[6:9], v[2:5], 0
	s_waitcnt lgkmcnt(0)
	v_mfma_f32_16x16x32_bf16 v[2:5], v[108:111], v[2:5], 0
	s_cbranch_vccz .LBB0_1166
	s_andn2_b64 vcc, exec, s[14:15]
	s_cbranch_vccz .LBB0_1167

.LBB0_1166:
	v_add_u32_e32 v68, s12, v107
	ds_read_b128 v[198:201], v68
	v_add_u32_e32 v68, s12, v89
	ds_read_b128 v[202:205], v68
	v_add_u32_e32 v68, s12, v88
	ds_read_b128 v[206:209], v68
	v_add_u32_e32 v68, s12, v87
	ds_read_b128 v[210:213], v68
	v_add_u32_e32 v68, s12, v86
	ds_read_b128 v[214:217], v68
	v_add_u32_e32 v68, s12, v85
	ds_read_b128 v[218:221], v68
	v_add_u32_e32 v68, s12, v84
	ds_read_b128 v[222:225], v68
	v_add_u32_e32 v68, s12, v83
	ds_read_b128 v[226:229], v68
	s_waitcnt vmcnt(11) lgkmcnt(7)
	v_mfma_f32_16x16x32_bf16 v[30:33], v[198:201], v[234:237], v[30:33]
	s_waitcnt lgkmcnt(6)
	v_mfma_f32_16x16x32_bf16 v[26:29], v[202:205], v[234:237], v[26:29]
	s_waitcnt lgkmcnt(5)
	v_mfma_f32_16x16x32_bf16 v[22:25], v[206:209], v[234:237], v[22:25]
	s_waitcnt lgkmcnt(4)
	v_mfma_f32_16x16x32_bf16 v[18:21], v[210:213], v[234:237], v[18:21]
	s_waitcnt lgkmcnt(3)
	v_mfma_f32_16x16x32_bf16 v[14:17], v[214:217], v[234:237], v[14:17]
	s_waitcnt lgkmcnt(2)
	v_mfma_f32_16x16x32_bf16 v[10:13], v[218:221], v[234:237], v[10:13]
	s_waitcnt lgkmcnt(1)
	v_mfma_f32_16x16x32_bf16 v[6:9], v[222:225], v[234:237], v[6:9]
	s_waitcnt lgkmcnt(0)
	v_mfma_f32_16x16x32_bf16 v[2:5], v[226:229], v[234:237], v[2:5]
	s_andn2_b64 vcc, exec, s[14:15]
	s_cbranch_vccnz .LBB0_1165
.LBB0_1167:
	v_add_u32_e32 v68, s12, v106
	ds_read_b128 v[198:201], v68
	v_add_u32_e32 v68, s12, v82
	ds_read_b128 v[202:205], v68
	v_add_u32_e32 v68, s12, v81
	ds_read_b128 v[206:209], v68
	v_add_u32_e32 v68, s12, v80
	ds_read_b128 v[210:213], v68
	v_add_u32_e32 v68, s12, v79
	ds_read_b128 v[214:217], v68
	v_add_u32_e32 v68, s12, v78
	ds_read_b128 v[218:221], v68
	v_add_u32_e32 v68, s12, v77
	ds_read_b128 v[222:225], v68
	v_add_u32_e32 v68, s12, v76
	ds_read_b128 v[226:229], v68
	s_waitcnt vmcnt(1) lgkmcnt(7)
	v_mfma_f32_16x16x32_bf16 v[30:33], v[198:201], v[38:41], v[30:33]
	s_waitcnt lgkmcnt(6)
	v_mfma_f32_16x16x32_bf16 v[26:29], v[202:205], v[38:41], v[26:29]
	s_waitcnt lgkmcnt(5)
	v_mfma_f32_16x16x32_bf16 v[22:25], v[206:209], v[38:41], v[22:25]
	s_waitcnt lgkmcnt(4)
	v_mfma_f32_16x16x32_bf16 v[18:21], v[210:213], v[38:41], v[18:21]
	s_waitcnt lgkmcnt(3)
	v_mfma_f32_16x16x32_bf16 v[14:17], v[214:217], v[38:41], v[14:17]
	s_waitcnt lgkmcnt(2)
	v_mfma_f32_16x16x32_bf16 v[10:13], v[218:221], v[38:41], v[10:13]
	s_waitcnt lgkmcnt(1)
	v_mfma_f32_16x16x32_bf16 v[6:9], v[222:225], v[38:41], v[6:9]
	s_waitcnt lgkmcnt(0)
	v_mfma_f32_16x16x32_bf16 v[2:5], v[226:229], v[38:41], v[2:5]
	s_andn2_b64 vcc, exec, s[16:17]
	s_cbranch_vccnz .LBB0_1162
.LBB0_1168:
	v_add_u32_e32 v38, s12, v105
	ds_read_b128 v[198:201], v38
	v_add_u32_e32 v38, s12, v75
	ds_read_b128 v[202:205], v38
	v_add_u32_e32 v38, s12, v74
	ds_read_b128 v[206:209], v38
	v_add_u32_e32 v38, s12, v73
	ds_read_b128 v[210:213], v38
	v_add_u32_e32 v38, s12, v72
	ds_read_b128 v[214:217], v38
	v_add_u32_e32 v38, s12, v71
	ds_read_b128 v[218:221], v38
	v_add_u32_e32 v38, s12, v70
	ds_read_b128 v[222:225], v38
	v_add_u32_e32 v38, s12, v51
	ds_read_b128 v[226:229], v38
	s_waitcnt vmcnt(0) lgkmcnt(7)
	v_mfma_f32_16x16x32_bf16 v[30:33], v[198:201], v[34:37], v[30:33]
	s_waitcnt lgkmcnt(6)
	v_mfma_f32_16x16x32_bf16 v[26:29], v[202:205], v[34:37], v[26:29]
	s_waitcnt lgkmcnt(5)
	v_mfma_f32_16x16x32_bf16 v[22:25], v[206:209], v[34:37], v[22:25]
	s_waitcnt lgkmcnt(4)
	v_mfma_f32_16x16x32_bf16 v[18:21], v[210:213], v[34:37], v[18:21]
	s_waitcnt lgkmcnt(3)
	v_mfma_f32_16x16x32_bf16 v[14:17], v[214:217], v[34:37], v[14:17]
	s_waitcnt lgkmcnt(2)
	v_mfma_f32_16x16x32_bf16 v[10:13], v[218:221], v[34:37], v[10:13]
	s_waitcnt lgkmcnt(1)
	v_mfma_f32_16x16x32_bf16 v[6:9], v[222:225], v[34:37], v[6:9]
	s_waitcnt lgkmcnt(0)
	v_mfma_f32_16x16x32_bf16 v[2:5], v[226:229], v[34:37], v[2:5]
	s_branch .LBB0_1162

.LBB0_1238:
	s_or_b64 exec, exec, s[6:7]
	v_mul_u32_u24_e32 v2, 0x110, v163
	v_add3_u32 v30, 0, v160, v2
	ds_read_b128 v[198:201], v30
	ds_read_b128 v[202:205], v30 offset:32
	ds_read_b128 v[206:209], v30 offset:64
	ds_read_b128 v[210:213], v30 offset:96
	ds_read_b128 v[214:217], v30 offset:128
	ds_read_b128 v[218:221], v30 offset:160
	ds_read_b128 v[222:225], v30 offset:192
	ds_read_b128 v[226:229], v30 offset:224
	s_waitcnt vmcnt(0) lgkmcnt(7)
	v_mfma_f32_32x32x16_bf16 v[114:129], v[198:201], v[18:21], 0
	ds_read_b128 v[198:201], v30 offset:8704
	s_waitcnt lgkmcnt(7)
	v_mfma_f32_32x32x16_bf16 v[114:129], v[202:205], v[130:133], v[114:129]
	ds_read_b128 v[202:205], v30 offset:8736
	s_waitcnt lgkmcnt(7)
	v_mfma_f32_32x32x16_bf16 v[114:129], v[206:209], v[138:141], v[114:129]
	ds_read_b128 v[206:209], v30 offset:8768
	s_waitcnt lgkmcnt(7)
	v_mfma_f32_32x32x16_bf16 v[114:129], v[210:213], v[134:137], v[114:129]
	ds_read_b128 v[210:213], v30 offset:8800
	s_waitcnt lgkmcnt(7)
	v_mfma_f32_32x32x16_bf16 v[114:129], v[214:217], v[146:149], v[114:129]
	ds_read_b128 v[214:217], v30 offset:8832
	s_waitcnt lgkmcnt(7)
	v_mfma_f32_32x32x16_bf16 v[114:129], v[218:221], v[142:145], v[114:129]
	ds_read_b128 v[218:221], v30 offset:8864
	s_waitcnt lgkmcnt(7)
	v_mfma_f32_32x32x16_bf16 v[114:129], v[222:225], v[154:157], v[114:129]
	ds_read_b128 v[222:225], v30 offset:8896
	s_waitcnt lgkmcnt(7)
	v_mfma_f32_32x32x16_bf16 v[114:129], v[226:229], v[150:153], v[114:129]
	ds_read_b128 v[226:229], v30 offset:8928
	s_waitcnt lgkmcnt(7)
	v_mfma_f32_32x32x16_bf16 v[98:113], v[198:201], v[18:21], 0
	ds_read_b128 v[198:201], v30 offset:17408
	s_waitcnt lgkmcnt(7)
	v_mfma_f32_32x32x16_bf16 v[98:113], v[202:205], v[130:133], v[98:113]
	ds_read_b128 v[202:205], v30 offset:17440
	s_waitcnt lgkmcnt(7)
	v_mfma_f32_32x32x16_bf16 v[98:113], v[206:209], v[138:141], v[98:113]
	ds_read_b128 v[206:209], v30 offset:17472
	s_waitcnt lgkmcnt(7)
	v_mfma_f32_32x32x16_bf16 v[98:113], v[210:213], v[134:137], v[98:113]
	ds_read_b128 v[210:213], v30 offset:17504
	s_waitcnt lgkmcnt(7)
	v_mfma_f32_32x32x16_bf16 v[98:113], v[214:217], v[146:149], v[98:113]
	ds_read_b128 v[214:217], v30 offset:17536
	s_waitcnt lgkmcnt(7)
	v_mfma_f32_32x32x16_bf16 v[98:113], v[218:221], v[142:145], v[98:113]
	ds_read_b128 v[218:221], v30 offset:17568
	s_waitcnt lgkmcnt(7)
	v_mfma_f32_32x32x16_bf16 v[98:113], v[222:225], v[154:157], v[98:113]
	ds_read_b128 v[222:225], v30 offset:17600
	s_waitcnt lgkmcnt(7)
	v_mfma_f32_32x32x16_bf16 v[98:113], v[226:229], v[150:153], v[98:113]
	ds_read_b128 v[226:229], v30 offset:17632
	s_waitcnt lgkmcnt(7)
	v_mfma_f32_32x32x16_bf16 v[82:97], v[198:201], v[18:21], 0
	ds_read_b128 v[198:201], v30 offset:26112
	s_waitcnt lgkmcnt(7)
	v_mfma_f32_32x32x16_bf16 v[82:97], v[202:205], v[130:133], v[82:97]
	ds_read_b128 v[202:205], v30 offset:26144
	s_waitcnt lgkmcnt(7)
	v_mfma_f32_32x32x16_bf16 v[82:97], v[206:209], v[138:141], v[82:97]
	ds_read_b128 v[206:209], v30 offset:26176
	s_waitcnt lgkmcnt(7)
	v_mfma_f32_32x32x16_bf16 v[82:97], v[210:213], v[134:137], v[82:97]
	ds_read_b128 v[210:213], v30 offset:26208
	s_waitcnt lgkmcnt(7)
	v_mfma_f32_32x32x16_bf16 v[82:97], v[214:217], v[146:149], v[82:97]
	ds_read_b128 v[214:217], v30 offset:26240
	s_waitcnt lgkmcnt(7)
	v_mfma_f32_32x32x16_bf16 v[82:97], v[218:221], v[142:145], v[82:97]
	ds_read_b128 v[218:221], v30 offset:26272
	s_waitcnt lgkmcnt(7)
	v_mfma_f32_32x32x16_bf16 v[82:97], v[222:225], v[154:157], v[82:97]
	ds_read_b128 v[222:225], v30 offset:26304
	s_waitcnt lgkmcnt(7)
	v_mfma_f32_32x32x16_bf16 v[82:97], v[226:229], v[150:153], v[82:97]
	ds_read_b128 v[226:229], v30 offset:26336
	s_waitcnt lgkmcnt(7)
	v_mfma_f32_32x32x16_bf16 v[66:81], v[198:201], v[18:21], 0
	ds_read_b128 v[198:201], v30 offset:34816
	s_waitcnt lgkmcnt(7)
	v_mfma_f32_32x32x16_bf16 v[66:81], v[202:205], v[130:133], v[66:81]
	ds_read_b128 v[202:205], v30 offset:34848
	s_waitcnt lgkmcnt(7)
	v_mfma_f32_32x32x16_bf16 v[66:81], v[206:209], v[138:141], v[66:81]
	ds_read_b128 v[206:209], v30 offset:34880
	s_waitcnt lgkmcnt(7)
	v_mfma_f32_32x32x16_bf16 v[66:81], v[210:213], v[134:137], v[66:81]
	ds_read_b128 v[210:213], v30 offset:34912
	s_waitcnt lgkmcnt(7)
	v_mfma_f32_32x32x16_bf16 v[66:81], v[214:217], v[146:149], v[66:81]
	ds_read_b128 v[214:217], v30 offset:34944
	s_waitcnt lgkmcnt(7)
	v_mfma_f32_32x32x16_bf16 v[66:81], v[218:221], v[142:145], v[66:81]
	ds_read_b128 v[218:221], v30 offset:34976
	s_waitcnt lgkmcnt(7)
	v_mfma_f32_32x32x16_bf16 v[66:81], v[222:225], v[154:157], v[66:81]
	ds_read_b128 v[222:225], v30 offset:35008
	s_waitcnt lgkmcnt(7)
	v_mfma_f32_32x32x16_bf16 v[66:81], v[226:229], v[150:153], v[66:81]
	ds_read_b128 v[226:229], v30 offset:35040
	s_waitcnt lgkmcnt(7)
	v_mfma_f32_32x32x16_bf16 v[50:65], v[198:201], v[18:21], 0
	ds_read_b128 v[198:201], v30 offset:43520
	s_waitcnt lgkmcnt(7)
	v_mfma_f32_32x32x16_bf16 v[50:65], v[202:205], v[130:133], v[50:65]
	ds_read_b128 v[202:205], v30 offset:43552
	s_waitcnt lgkmcnt(7)
	v_mfma_f32_32x32x16_bf16 v[50:65], v[206:209], v[138:141], v[50:65]
	ds_read_b128 v[206:209], v30 offset:43584
	s_waitcnt lgkmcnt(7)
	v_mfma_f32_32x32x16_bf16 v[50:65], v[210:213], v[134:137], v[50:65]
	ds_read_b128 v[210:213], v30 offset:43616
	s_waitcnt lgkmcnt(7)
	v_mfma_f32_32x32x16_bf16 v[50:65], v[214:217], v[146:149], v[50:65]
	ds_read_b128 v[214:217], v30 offset:43648
	s_waitcnt lgkmcnt(7)
	v_mfma_f32_32x32x16_bf16 v[50:65], v[218:221], v[142:145], v[50:65]
	ds_read_b128 v[218:221], v30 offset:43680
	s_waitcnt lgkmcnt(7)
	v_mfma_f32_32x32x16_bf16 v[50:65], v[222:225], v[154:157], v[50:65]
	ds_read_b128 v[222:225], v30 offset:43712
	s_waitcnt lgkmcnt(7)
	v_mfma_f32_32x32x16_bf16 v[50:65], v[226:229], v[150:153], v[50:65]
	ds_read_b128 v[226:229], v30 offset:43744
	s_waitcnt lgkmcnt(7)
	v_mfma_f32_32x32x16_bf16 v[34:49], v[198:201], v[18:21], 0
	ds_read_b128 v[198:201], v30 offset:52224
	s_waitcnt lgkmcnt(7)
	v_mfma_f32_32x32x16_bf16 v[34:49], v[202:205], v[130:133], v[34:49]
	ds_read_b128 v[202:205], v30 offset:52256
	s_waitcnt lgkmcnt(7)
	v_mfma_f32_32x32x16_bf16 v[34:49], v[206:209], v[138:141], v[34:49]
	ds_read_b128 v[206:209], v30 offset:52288
	s_waitcnt lgkmcnt(7)
	v_mfma_f32_32x32x16_bf16 v[34:49], v[210:213], v[134:137], v[34:49]
	ds_read_b128 v[210:213], v30 offset:52320
	s_waitcnt lgkmcnt(7)
	v_mfma_f32_32x32x16_bf16 v[34:49], v[214:217], v[146:149], v[34:49]
	ds_read_b128 v[214:217], v30 offset:52352
	s_waitcnt lgkmcnt(7)
	v_mfma_f32_32x32x16_bf16 v[34:49], v[218:221], v[142:145], v[34:49]
	ds_read_b128 v[218:221], v30 offset:52384
	s_waitcnt lgkmcnt(7)
	v_mfma_f32_32x32x16_bf16 v[34:49], v[222:225], v[154:157], v[34:49]
	ds_read_b128 v[222:225], v30 offset:52416
	s_waitcnt lgkmcnt(7)
	v_mfma_f32_32x32x16_bf16 v[34:49], v[226:229], v[150:153], v[34:49]
	ds_read_b128 v[226:229], v30 offset:52448
	ds_read_b128 v[22:25], v30 offset:60928
	ds_read_b128 v[166:169], v30 offset:60960
	ds_read_b128 v[170:173], v30 offset:60992
	ds_read_b128 v[174:177], v30 offset:61024
	ds_read_b128 v[178:181], v30 offset:61056
	ds_read_b128 v[182:185], v30 offset:61088
	ds_read_b128 v[186:189], v30 offset:61120
	ds_read_b128 v[190:193], v30 offset:61152
	s_waitcnt lgkmcnt(15)
	v_mfma_f32_32x32x16_bf16 v[2:17], v[198:201], v[18:21], 0
	s_waitcnt lgkmcnt(14)
	v_mfma_f32_32x32x16_bf16 v[2:17], v[202:205], v[130:133], v[2:17]
	s_waitcnt lgkmcnt(13)
	v_mfma_f32_32x32x16_bf16 v[2:17], v[206:209], v[138:141], v[2:17]
	s_waitcnt lgkmcnt(12)
	v_mfma_f32_32x32x16_bf16 v[2:17], v[210:213], v[134:137], v[2:17]
	s_waitcnt lgkmcnt(11)
	v_mfma_f32_32x32x16_bf16 v[2:17], v[214:217], v[146:149], v[2:17]
	s_waitcnt lgkmcnt(10)
	v_mfma_f32_32x32x16_bf16 v[2:17], v[218:221], v[142:145], v[2:17]
	s_waitcnt lgkmcnt(9)
	v_mfma_f32_32x32x16_bf16 v[2:17], v[222:225], v[154:157], v[2:17]
	s_waitcnt lgkmcnt(8)
	v_mfma_f32_32x32x16_bf16 v[2:17], v[226:229], v[150:153], v[2:17]
	v_max3_f32 v26, v114, s8, v115
	v_max3_f32 v26, v26, v116, v117
	v_max3_f32 v26, v26, v118, v119
	v_max3_f32 v26, v26, v120, v121
	v_max3_f32 v26, v26, v122, v123
	v_max3_f32 v26, v26, v124, v125
	v_max3_f32 v158, v26, v126, v127
	s_waitcnt lgkmcnt(7)
	v_mfma_f32_32x32x16_bf16 v[18:33], v[22:25], v[18:21], 0
	v_max3_f32 v158, v158, v128, v129
	v_max3_f32 v158, v158, v98, v99
	v_max3_f32 v158, v158, v100, v101
	v_max3_f32 v158, v158, v102, v103
	v_max3_f32 v158, v158, v104, v105
	v_max3_f32 v158, v158, v106, v107
	v_max3_f32 v158, v158, v108, v109
	s_waitcnt lgkmcnt(6)
	v_mfma_f32_32x32x16_bf16 v[18:33], v[166:169], v[130:133], v[18:33]
	v_max3_f32 v130, v158, v110, v111
	v_max3_f32 v130, v130, v112, v113
	v_max3_f32 v130, v130, v82, v83
	v_max3_f32 v130, v130, v84, v85
	v_max3_f32 v130, v130, v86, v87
	v_max3_f32 v130, v130, v88, v89
	v_max3_f32 v130, v130, v90, v91
	s_waitcnt lgkmcnt(5)
	v_mfma_f32_32x32x16_bf16 v[18:33], v[170:173], v[138:141], v[18:33]
	v_max3_f32 v130, v130, v92, v93
	v_max3_f32 v130, v130, v94, v95
	v_max3_f32 v130, v130, v96, v97
	v_max3_f32 v130, v130, v66, v67
	v_max3_f32 v130, v130, v68, v69
	v_max3_f32 v130, v130, v70, v71
	v_max3_f32 v130, v130, v72, v73
	s_waitcnt lgkmcnt(4)
	v_mfma_f32_32x32x16_bf16 v[18:33], v[174:177], v[134:137], v[18:33]
	v_max3_f32 v130, v130, v74, v75
	v_max3_f32 v130, v130, v76, v77
	v_max3_f32 v130, v130, v78, v79
	v_max3_f32 v130, v130, v80, v81
	v_max3_f32 v130, v130, v50, v51
	v_max3_f32 v130, v130, v52, v53
	v_max3_f32 v130, v130, v54, v55
	s_waitcnt lgkmcnt(3)
	v_mfma_f32_32x32x16_bf16 v[18:33], v[178:181], v[146:149], v[18:33]
	v_max3_f32 v130, v130, v56, v57
	v_max3_f32 v130, v130, v58, v59
	v_max3_f32 v130, v130, v60, v61
	v_max3_f32 v130, v130, v62, v63
	v_max3_f32 v130, v130, v64, v65
	v_max3_f32 v130, v130, v34, v35
	v_max3_f32 v130, v130, v36, v37
	s_waitcnt lgkmcnt(2)
	v_mfma_f32_32x32x16_bf16 v[18:33], v[182:185], v[142:145], v[18:33]
	v_max3_f32 v130, v130, v38, v39
	v_max3_f32 v130, v130, v40, v41
	v_max3_f32 v130, v130, v42, v43
	v_max3_f32 v130, v130, v44, v45
	v_max3_f32 v130, v130, v46, v47
	v_max3_f32 v130, v130, v48, v49
	v_max3_f32 v130, v130, v2, v3
	s_waitcnt lgkmcnt(1)
	v_mfma_f32_32x32x16_bf16 v[18:33], v[186:189], v[154:157], v[18:33]
	v_max3_f32 v130, v130, v4, v5
	v_max3_f32 v130, v130, v6, v7
	v_max3_f32 v130, v130, v8, v9
	v_max3_f32 v130, v130, v10, v11
	v_max3_f32 v130, v130, v12, v13
	v_max3_f32 v130, v130, v14, v15
	v_max3_f32 v130, v130, v16, v17
	s_waitcnt lgkmcnt(0)
	v_mfma_f32_32x32x16_bf16 v[18:33], v[190:193], v[150:153], v[18:33]
	v_and_b32_e32 v132, 64, v1
	v_xor_b32_e32 v131, 32, v1
	v_add_u32_e32 v132, 64, v132
	v_cmp_lt_i32_e32 vcc, v131, v132
	s_nop 1
	v_cndmask_b32_e32 v131, v1, v131, vcc
	s_nop 4
	v_max3_f32 v130, v130, v18, v19
	v_max3_f32 v130, v130, v20, v21
	v_max3_f32 v130, v130, v22, v23
	v_max3_f32 v130, v130, v24, v25
	v_max3_f32 v130, v130, v26, v27
	v_max3_f32 v130, v130, v28, v29
	v_max3_f32 v130, v130, v30, v31
	v_max3_f32 v130, v130, v32, v33
	v_lshlrev_b32_e32 v131, 2, v131
	ds_bpermute_b32 v132, v131, v130
	s_waitcnt lgkmcnt(0)
	v_max_f32_e32 v132, v132, v132
	v_max_f32_e32 v130, v130, v132
	v_sub_f32_e32 v114, v114, v130
	v_exp_f32_e32 v132, v114
	v_sub_f32_e32 v114, v115, v130
	v_exp_f32_e32 v133, v114
	v_sub_f32_e32 v114, v116, v130
	v_exp_f32_e32 v134, v114
	v_sub_f32_e32 v114, v117, v130
	v_exp_f32_e32 v135, v114
	v_sub_f32_e32 v114, v118, v130
	v_exp_f32_e32 v136, v114
	v_sub_f32_e32 v114, v119, v130
	v_exp_f32_e32 v137, v114
	v_sub_f32_e32 v114, v120, v130
	v_exp_f32_e32 v138, v114
	v_sub_f32_e32 v114, v121, v130
	v_exp_f32_e32 v139, v114
	v_sub_f32_e32 v114, v122, v130
	v_cvt_pk_bf16_f32 v118, v132, v133
	v_add_f32_e32 v132, 0, v132
	v_exp_f32_e32 v122, v114
	v_sub_f32_e32 v114, v123, v130
	v_add_f32_e32 v132, v133, v132
	v_exp_f32_e32 v123, v114
	v_sub_f32_e32 v114, v124, v130
	v_add_f32_e32 v132, v134, v132
	v_exp_f32_e32 v124, v114
	v_sub_f32_e32 v114, v125, v130
	v_add_f32_e32 v132, v135, v132
	v_exp_f32_e32 v125, v114
	v_sub_f32_e32 v114, v126, v130
	v_add_f32_e32 v132, v136, v132
	v_exp_f32_e32 v126, v114
	v_sub_f32_e32 v114, v127, v130
	v_add_f32_e32 v132, v137, v132
	v_exp_f32_e32 v127, v114
	v_sub_f32_e32 v114, v128, v130
	v_add_f32_e32 v132, v138, v132
	v_exp_f32_e32 v128, v114
	v_sub_f32_e32 v114, v129, v130
	v_add_f32_e32 v132, v139, v132
	v_exp_f32_e32 v129, v114
	v_cvt_pk_bf16_f32 v114, v122, v123
	v_add_f32_e32 v122, v122, v132
	v_sub_f32_e32 v98, v98, v130
	v_add_f32_e32 v122, v123, v122
	v_exp_f32_e32 v123, v98
	v_sub_f32_e32 v98, v99, v130
	v_cvt_pk_bf16_f32 v115, v124, v125
	v_add_f32_e32 v122, v124, v122
	v_exp_f32_e32 v124, v98
	v_sub_f32_e32 v98, v100, v130
	v_add_f32_e32 v122, v125, v122
	v_exp_f32_e32 v125, v98
	v_sub_f32_e32 v98, v101, v130
	v_cvt_pk_bf16_f32 v116, v126, v127
	v_add_f32_e32 v122, v126, v122
	v_exp_f32_e32 v126, v98
	v_sub_f32_e32 v98, v102, v130
	v_add_f32_e32 v122, v127, v122
	v_exp_f32_e32 v127, v98
	v_sub_f32_e32 v98, v103, v130
	v_cvt_pk_bf16_f32 v117, v128, v129
	v_add_f32_e32 v122, v128, v122
	v_exp_f32_e32 v128, v98
	v_sub_f32_e32 v98, v104, v130
	v_add_f32_e32 v122, v129, v122
	v_exp_f32_e32 v129, v98
	v_sub_f32_e32 v98, v105, v130
	v_exp_f32_e32 v132, v98
	v_sub_f32_e32 v98, v106, v130
	v_add_f32_e32 v122, v123, v122
	v_exp_f32_e32 v106, v98
	v_sub_f32_e32 v98, v107, v130
	v_add_f32_e32 v122, v124, v122
	v_exp_f32_e32 v107, v98
	v_sub_f32_e32 v98, v108, v130
	v_add_f32_e32 v122, v125, v122
	v_exp_f32_e32 v108, v98
	v_sub_f32_e32 v98, v109, v130
	v_add_f32_e32 v122, v126, v122
	v_exp_f32_e32 v109, v98
	v_sub_f32_e32 v98, v110, v130
	v_add_f32_e32 v122, v127, v122
	v_exp_f32_e32 v110, v98
	v_sub_f32_e32 v98, v111, v130
	v_add_f32_e32 v122, v128, v122
	v_exp_f32_e32 v111, v98
	v_sub_f32_e32 v98, v112, v130
	v_add_f32_e32 v122, v129, v122
	v_exp_f32_e32 v112, v98
	v_sub_f32_e32 v98, v113, v130
	v_add_f32_e32 v122, v132, v122
	v_exp_f32_e32 v113, v98
	v_cvt_pk_bf16_f32 v98, v106, v107
	v_add_f32_e32 v106, v106, v122
	v_sub_f32_e32 v82, v82, v130
	v_add_f32_e32 v106, v107, v106
	v_exp_f32_e32 v107, v82
	v_sub_f32_e32 v82, v83, v130
	v_cvt_pk_bf16_f32 v99, v108, v109
	v_add_f32_e32 v106, v108, v106
	v_exp_f32_e32 v108, v82
	v_sub_f32_e32 v82, v84, v130
	v_add_f32_e32 v106, v109, v106
	v_exp_f32_e32 v109, v82
	v_sub_f32_e32 v82, v85, v130
	v_cvt_pk_bf16_f32 v100, v110, v111
	v_add_f32_e32 v106, v110, v106
	v_exp_f32_e32 v110, v82
	v_sub_f32_e32 v82, v86, v130
	v_add_f32_e32 v106, v111, v106
	v_exp_f32_e32 v111, v82
	v_sub_f32_e32 v82, v87, v130
	v_cvt_pk_bf16_f32 v101, v112, v113
	v_add_f32_e32 v106, v112, v106
	v_exp_f32_e32 v112, v82
	v_sub_f32_e32 v82, v88, v130
	v_add_f32_e32 v106, v113, v106
	v_exp_f32_e32 v113, v82
	v_sub_f32_e32 v82, v89, v130
	v_exp_f32_e32 v122, v82
	v_sub_f32_e32 v82, v90, v130
	v_add_f32_e32 v106, v107, v106
	v_exp_f32_e32 v90, v82
	v_sub_f32_e32 v82, v91, v130
	v_add_f32_e32 v106, v108, v106
	v_exp_f32_e32 v91, v82
	v_sub_f32_e32 v82, v92, v130
	v_add_f32_e32 v106, v109, v106
	v_exp_f32_e32 v92, v82
	v_sub_f32_e32 v82, v93, v130
	v_add_f32_e32 v106, v110, v106
	v_exp_f32_e32 v93, v82
	v_sub_f32_e32 v82, v94, v130
	v_add_f32_e32 v106, v111, v106
	v_exp_f32_e32 v94, v82
	v_sub_f32_e32 v82, v95, v130
	v_add_f32_e32 v106, v112, v106
	v_exp_f32_e32 v95, v82
	v_sub_f32_e32 v82, v96, v130
	v_add_f32_e32 v106, v113, v106
	v_exp_f32_e32 v96, v82
	v_sub_f32_e32 v82, v97, v130
	v_add_f32_e32 v106, v122, v106
	v_exp_f32_e32 v97, v82
	v_cvt_pk_bf16_f32 v82, v90, v91
	v_add_f32_e32 v90, v90, v106
	v_sub_f32_e32 v66, v66, v130
	v_add_f32_e32 v90, v91, v90
	v_exp_f32_e32 v91, v66
	v_sub_f32_e32 v66, v67, v130
	v_cvt_pk_bf16_f32 v83, v92, v93
	v_add_f32_e32 v90, v92, v90
	v_exp_f32_e32 v92, v66
	v_sub_f32_e32 v66, v68, v130
	v_add_f32_e32 v90, v93, v90
	v_exp_f32_e32 v93, v66
	v_sub_f32_e32 v66, v69, v130
	v_cvt_pk_bf16_f32 v84, v94, v95
	v_add_f32_e32 v90, v94, v90
	v_exp_f32_e32 v94, v66
	v_sub_f32_e32 v66, v70, v130
	v_add_f32_e32 v90, v95, v90
	v_exp_f32_e32 v95, v66
	v_sub_f32_e32 v66, v71, v130
	v_cvt_pk_bf16_f32 v85, v96, v97
	v_add_f32_e32 v90, v96, v90
	v_exp_f32_e32 v96, v66
	v_sub_f32_e32 v66, v72, v130
	v_add_f32_e32 v90, v97, v90
	v_exp_f32_e32 v97, v66
	v_sub_f32_e32 v66, v73, v130
	v_exp_f32_e32 v106, v66
	v_sub_f32_e32 v66, v74, v130
	v_add_f32_e32 v90, v91, v90
	v_exp_f32_e32 v74, v66
	v_sub_f32_e32 v66, v75, v130
	v_add_f32_e32 v90, v92, v90
	v_exp_f32_e32 v75, v66
	v_sub_f32_e32 v66, v76, v130
	v_add_f32_e32 v90, v93, v90
	v_exp_f32_e32 v76, v66
	v_sub_f32_e32 v66, v77, v130
	v_add_f32_e32 v90, v94, v90
	v_exp_f32_e32 v77, v66
	v_sub_f32_e32 v66, v78, v130
	v_add_f32_e32 v90, v95, v90
	v_exp_f32_e32 v78, v66
	v_sub_f32_e32 v66, v79, v130
	v_add_f32_e32 v90, v96, v90
	v_exp_f32_e32 v79, v66
	v_sub_f32_e32 v66, v80, v130
	v_add_f32_e32 v90, v97, v90
	v_exp_f32_e32 v80, v66
	v_sub_f32_e32 v66, v81, v130
	v_add_f32_e32 v90, v106, v90
	v_exp_f32_e32 v81, v66
	v_cvt_pk_bf16_f32 v66, v74, v75
	v_add_f32_e32 v74, v74, v90
	v_sub_f32_e32 v50, v50, v130
	v_add_f32_e32 v74, v75, v74
	v_exp_f32_e32 v75, v50
	v_sub_f32_e32 v50, v51, v130
	v_cvt_pk_bf16_f32 v67, v76, v77
	v_add_f32_e32 v74, v76, v74
	v_exp_f32_e32 v76, v50
	v_sub_f32_e32 v50, v52, v130
	v_add_f32_e32 v74, v77, v74
	v_exp_f32_e32 v77, v50
	v_sub_f32_e32 v50, v53, v130
	v_cvt_pk_bf16_f32 v68, v78, v79
	v_add_f32_e32 v74, v78, v74
	v_exp_f32_e32 v78, v50
	v_sub_f32_e32 v50, v54, v130
	v_add_f32_e32 v74, v79, v74
	v_exp_f32_e32 v79, v50
	v_sub_f32_e32 v50, v55, v130
	v_cvt_pk_bf16_f32 v69, v80, v81
	v_add_f32_e32 v74, v80, v74
	v_exp_f32_e32 v80, v50
	v_sub_f32_e32 v50, v56, v130
	v_add_f32_e32 v74, v81, v74
	v_exp_f32_e32 v81, v50
	v_sub_f32_e32 v50, v57, v130
	v_exp_f32_e32 v90, v50
	v_sub_f32_e32 v50, v58, v130
	v_add_f32_e32 v74, v75, v74
	v_exp_f32_e32 v58, v50
	v_sub_f32_e32 v50, v59, v130
	v_add_f32_e32 v74, v76, v74
	v_exp_f32_e32 v59, v50
	v_sub_f32_e32 v50, v60, v130
	v_add_f32_e32 v74, v77, v74
	v_exp_f32_e32 v60, v50
	v_sub_f32_e32 v50, v61, v130
	v_add_f32_e32 v74, v78, v74
	v_exp_f32_e32 v61, v50
	v_sub_f32_e32 v50, v62, v130
	v_add_f32_e32 v74, v79, v74
	v_exp_f32_e32 v62, v50
	v_sub_f32_e32 v50, v63, v130
	v_add_f32_e32 v74, v80, v74
	v_exp_f32_e32 v63, v50
	v_sub_f32_e32 v50, v64, v130
	v_add_f32_e32 v74, v81, v74
	v_exp_f32_e32 v64, v50
	v_sub_f32_e32 v50, v65, v130
	v_add_f32_e32 v74, v90, v74
	v_exp_f32_e32 v65, v50
	v_cvt_pk_bf16_f32 v50, v58, v59
	v_add_f32_e32 v58, v58, v74
	v_sub_f32_e32 v34, v34, v130
	v_add_f32_e32 v58, v59, v58
	v_exp_f32_e32 v59, v34
	v_sub_f32_e32 v34, v35, v130
	v_cvt_pk_bf16_f32 v51, v60, v61
	v_add_f32_e32 v58, v60, v58
	v_exp_f32_e32 v60, v34
	v_sub_f32_e32 v34, v36, v130
	v_add_f32_e32 v58, v61, v58
	v_exp_f32_e32 v61, v34
	v_sub_f32_e32 v34, v37, v130
	v_cvt_pk_bf16_f32 v52, v62, v63
	v_add_f32_e32 v58, v62, v58
	v_exp_f32_e32 v62, v34
	v_sub_f32_e32 v34, v38, v130
	v_add_f32_e32 v58, v63, v58
	v_exp_f32_e32 v63, v34
	v_sub_f32_e32 v34, v39, v130
	v_cvt_pk_bf16_f32 v53, v64, v65
	v_add_f32_e32 v58, v64, v58
	v_exp_f32_e32 v64, v34
	v_sub_f32_e32 v34, v40, v130
	v_add_f32_e32 v58, v65, v58
	v_exp_f32_e32 v65, v34
	v_sub_f32_e32 v34, v41, v130
	v_exp_f32_e32 v74, v34
	v_sub_f32_e32 v34, v42, v130
	v_add_f32_e32 v58, v59, v58
	v_exp_f32_e32 v42, v34
	v_sub_f32_e32 v34, v43, v130
	v_add_f32_e32 v58, v60, v58
	v_exp_f32_e32 v43, v34
	v_sub_f32_e32 v34, v44, v130
	v_add_f32_e32 v58, v61, v58
	v_exp_f32_e32 v44, v34
	v_sub_f32_e32 v34, v45, v130
	v_add_f32_e32 v58, v62, v58
	v_exp_f32_e32 v45, v34
	v_sub_f32_e32 v34, v46, v130
	v_add_f32_e32 v58, v63, v58
	v_exp_f32_e32 v46, v34
	v_sub_f32_e32 v34, v47, v130
	v_add_f32_e32 v58, v64, v58
	v_exp_f32_e32 v47, v34
	v_sub_f32_e32 v34, v48, v130
	v_add_f32_e32 v58, v65, v58
	v_exp_f32_e32 v48, v34
	v_sub_f32_e32 v34, v49, v130
	v_add_f32_e32 v58, v74, v58
	v_exp_f32_e32 v49, v34
	v_cvt_pk_bf16_f32 v34, v42, v43
	v_add_f32_e32 v42, v42, v58
	v_add_f32_e32 v42, v43, v42
	v_add_f32_e32 v42, v44, v42
	v_add_f32_e32 v42, v45, v42
	v_sub_f32_e32 v2, v2, v130
	v_sub_f32_e32 v3, v3, v130
	v_add_f32_e32 v42, v46, v42
	v_exp_f32_e32 v2, v2
	v_exp_f32_e32 v3, v3
	v_add_f32_e32 v42, v47, v42
	v_sub_f32_e32 v4, v4, v130
	v_add_f32_e32 v42, v48, v42
	v_exp_f32_e32 v4, v4
	v_sub_f32_e32 v5, v5, v130
	v_add_f32_e32 v58, v49, v42
	v_exp_f32_e32 v5, v5
	v_sub_f32_e32 v6, v6, v130
	v_cvt_pk_bf16_f32 v36, v46, v47
	v_exp_f32_e32 v6, v6
	v_sub_f32_e32 v7, v7, v130
	v_cvt_pk_bf16_f32 v46, v2, v3
	v_add_f32_e32 v2, v2, v58
	v_exp_f32_e32 v7, v7
	v_sub_f32_e32 v8, v8, v130
	v_add_f32_e32 v2, v3, v2
	v_exp_f32_e32 v8, v8
	v_sub_f32_e32 v9, v9, v130
	v_add_f32_e32 v2, v4, v2
	v_exp_f32_e32 v9, v9
	v_sub_f32_e32 v10, v10, v130
	v_add_f32_e32 v2, v5, v2
	v_exp_f32_e32 v10, v10
	v_sub_f32_e32 v11, v11, v130
	v_add_f32_e32 v2, v6, v2
	v_exp_f32_e32 v11, v11
	v_sub_f32_e32 v12, v12, v130
	v_add_f32_e32 v2, v7, v2
	v_exp_f32_e32 v12, v12
	v_sub_f32_e32 v13, v13, v130
	v_add_f32_e32 v2, v8, v2
	v_exp_f32_e32 v13, v13
	v_sub_f32_e32 v14, v14, v130
	v_add_f32_e32 v2, v9, v2
	v_exp_f32_e32 v14, v14
	v_sub_f32_e32 v15, v15, v130
	v_add_f32_e32 v2, v10, v2
	v_exp_f32_e32 v15, v15
	v_sub_f32_e32 v16, v16, v130
	v_add_f32_e32 v2, v11, v2
	v_exp_f32_e32 v16, v16
	v_sub_f32_e32 v17, v17, v130
	v_add_f32_e32 v2, v12, v2
	v_exp_f32_e32 v17, v17
	v_add_f32_e32 v2, v13, v2
	v_sub_f32_e32 v3, v18, v130
	v_cvt_pk_bf16_f32 v47, v4, v5
	v_add_f32_e32 v2, v14, v2
	v_exp_f32_e32 v3, v3
	v_sub_f32_e32 v4, v19, v130
	v_add_f32_e32 v2, v15, v2
	v_exp_f32_e32 v4, v4
	v_sub_f32_e32 v5, v20, v130
	v_cvt_pk_bf16_f32 v37, v48, v49
	v_cvt_pk_bf16_f32 v48, v6, v7
	v_add_f32_e32 v2, v16, v2
	v_exp_f32_e32 v5, v5
	v_sub_f32_e32 v6, v21, v130
	v_add_f32_e32 v2, v17, v2
	v_exp_f32_e32 v6, v6
	v_sub_f32_e32 v7, v22, v130
	v_cvt_pk_bf16_f32 v49, v8, v9
	v_exp_f32_e32 v7, v7
	v_sub_f32_e32 v8, v23, v130
	v_add_f32_e32 v2, v3, v2
	v_exp_f32_e32 v8, v8
	v_sub_f32_e32 v9, v24, v130
	v_add_f32_e32 v2, v4, v2
	v_cvt_pk_bf16_f32 v42, v10, v11
	v_exp_f32_e32 v9, v9
	v_sub_f32_e32 v10, v25, v130
	v_add_f32_e32 v2, v5, v2
	v_exp_f32_e32 v10, v10
	v_sub_f32_e32 v11, v26, v130
	v_add_f32_e32 v2, v6, v2
	v_cvt_pk_bf16_f32 v43, v12, v13
	v_exp_f32_e32 v11, v11
	v_sub_f32_e32 v12, v27, v130
	v_add_f32_e32 v2, v7, v2
	v_exp_f32_e32 v12, v12
	v_sub_f32_e32 v13, v28, v130
	v_add_f32_e32 v2, v8, v2
	v_cvt_pk_bf16_f32 v35, v44, v45
	v_cvt_pk_bf16_f32 v44, v14, v15
	v_exp_f32_e32 v13, v13
	v_sub_f32_e32 v14, v29, v130
	v_add_f32_e32 v2, v9, v2
	v_exp_f32_e32 v14, v14
	v_sub_f32_e32 v15, v30, v130
	v_add_f32_e32 v2, v10, v2
	v_cvt_pk_bf16_f32 v45, v16, v17
	v_exp_f32_e32 v15, v15
	v_sub_f32_e32 v16, v31, v130
	v_add_f32_e32 v2, v11, v2
	v_exp_f32_e32 v16, v16
	v_sub_f32_e32 v17, v32, v130
	v_add_f32_e32 v2, v12, v2
	v_exp_f32_e32 v17, v17
	v_sub_f32_e32 v18, v33, v130
	v_add_f32_e32 v2, v13, v2
	v_exp_f32_e32 v18, v18
	v_add_f32_e32 v2, v14, v2
	v_add_f32_e32 v2, v15, v2
	v_add_f32_e32 v2, v16, v2
	v_add_f32_e32 v2, v17, v2
	v_add_f32_e32 v2, v18, v2
	v_cvt_pk_bf16_f32 v58, v3, v4
	ds_bpermute_b32 v3, v131, v2
	v_cvt_pk_bf16_f32 v38, v59, v60
	v_cvt_pk_bf16_f32 v59, v5, v6
	v_cvt_pk_bf16_f32 v60, v7, v8
	v_cvt_pk_bf16_f32 v119, v134, v135
	s_waitcnt lgkmcnt(0)
	v_add_f32_e32 v2, v2, v3
	v_div_scale_f32 v3, s[6:7], v2, v2, 1.0
	v_rcp_f32_e32 v4, v3
	v_cvt_pk_bf16_f32 v120, v136, v137
	v_cvt_pk_bf16_f32 v121, v138, v139
	v_cvt_pk_bf16_f32 v102, v123, v124
	v_fma_f32 v5, -v3, v4, 1.0
	v_fmac_f32_e32 v4, v5, v4
	v_div_scale_f32 v5, vcc, 1.0, v2, 1.0
	v_mul_f32_e32 v6, v5, v4
	v_fma_f32 v7, -v3, v6, v5
	v_fmac_f32_e32 v6, v7, v4
	v_fma_f32 v3, -v3, v6, v5
	v_div_fmas_f32 v3, v3, v4, v6
	v_cvt_pk_bf16_f32 v103, v125, v126
	v_cvt_pk_bf16_f32 v104, v127, v128
	v_cvt_pk_bf16_f32 v105, v129, v132
	v_cvt_pk_bf16_f32 v86, v107, v108
	v_cvt_pk_bf16_f32 v87, v109, v110
	v_cvt_pk_bf16_f32 v88, v111, v112
	v_cvt_pk_bf16_f32 v89, v113, v122
	v_cvt_pk_bf16_f32 v70, v91, v92
	v_cvt_pk_bf16_f32 v71, v93, v94
	v_cvt_pk_bf16_f32 v72, v95, v96
	v_cvt_pk_bf16_f32 v73, v97, v106
	v_cvt_pk_bf16_f32 v54, v75, v76
	v_cvt_pk_bf16_f32 v55, v77, v78
	v_cvt_pk_bf16_f32 v56, v79, v80
	v_cvt_pk_bf16_f32 v57, v81, v90
	v_cvt_pk_bf16_f32 v39, v61, v62
	v_cvt_pk_bf16_f32 v40, v63, v64
	v_cvt_pk_bf16_f32 v41, v65, v74
	v_cvt_pk_bf16_f32 v61, v9, v10
	v_cvt_pk_bf16_f32 v62, v11, v12
	v_cvt_pk_bf16_f32 v63, v13, v14
	v_cvt_pk_bf16_f32 v64, v15, v16
	v_cvt_pk_bf16_f32 v65, v17, v18
	v_div_fixup_f32 v74, v3, v2, 1.0
